# P1: next row x loads in flight while current row is normalised (A/B buffers)
# baseline (speedup 1.0000x reference)
; __global__ void __launch_bounds__(512, 2) fwd_megakernel(Params p) {
;     ...
;         for (int R = gw; R < NTOK + NCTX; R += NGW) {
;             const float* src = R < NTOK ? p.x + (size_t)R * DM : p.ctx + (size_t)(R - NTOK) * DM;
;             const float* mr = mod + (R < NTOK ? (R >> 13) : 4) * 6144;
;             f32x4 v[8]; float ss = 0.f;
; #pragma unroll
;             for (int j = 0; j < 8; ++j) { v[j] = __builtin_nontemporal_load((const f32x4*)(src + j * 256 + lane * 4)); ss += (v[j].x * v[j].x + v[j].y * v[j].y) + (v[j].z * v[j].z + v[j].w * v[j].w); }
.LBB0_57:
	s_or_b64 exec, exec, s[6:7]
	s_mov_b64 s[6:7], 0
	v_mov_b32_e32 v0, v200
	s_barrier
	v_mbcnt_lo_u32_b32 v201, -1, 0
	v_readfirstlane_b32 s0, v0
	s_ashr_i32 s0, s0, 6
	s_add_i32 s1, s0, s2
	s_cmp_gt_i32 s1, 0x83ff
	s_cbranch_scc1 .LBB0_62
	v_mbcnt_hi_u32_b32 v1, -1, v201
	v_and_b32_e32 v2, 64, v1
	v_add_u32_e32 v2, 64, v2
	v_xor_b32_e32 v3, 1, v1
	v_cmp_lt_i32_e32 vcc, v3, v2
	v_lshlrev_b32_e32 v0, 2, v0
	v_and_b32_e32 v0, 0xfc, v0
	v_cndmask_b32_e32 v3, v1, v3, vcc
	v_lshlrev_b32_e32 v42, 2, v3
	v_xor_b32_e32 v3, 2, v1
	v_cmp_lt_i32_e32 vcc, v3, v2
	v_mov_b32_e32 v29, 0
	v_lshlrev_b32_e32 v28, 2, v0
	v_cndmask_b32_e32 v3, v1, v3, vcc
	v_lshlrev_b32_e32 v43, 2, v3
	v_xor_b32_e32 v3, 4, v1
	v_cmp_lt_i32_e32 vcc, v3, v2
	v_or_b32_e32 v8, 0x400, v0
	v_lshl_add_u64 v[30:31], s[44:45], 0, v[28:29]
	v_cndmask_b32_e32 v3, v1, v3, vcc
	v_lshlrev_b32_e32 v28, 2, v8
	v_or_b32_e32 v10, 0x500, v0
	v_lshlrev_b32_e32 v44, 2, v3
	v_xor_b32_e32 v3, 8, v1
	v_lshl_add_u64 v[32:33], s[44:45], 0, v[28:29]
	v_lshlrev_b32_e32 v28, 2, v10
	v_or_b32_e32 v12, 0x600, v0
	v_cmp_lt_i32_e32 vcc, v3, v2
	v_lshl_add_u64 v[34:35], s[44:45], 0, v[28:29]
	v_lshlrev_b32_e32 v28, 2, v12
	v_or_b32_e32 v14, 0x700, v0
	s_add_u32 s6, s86, s6
	v_cndmask_b32_e32 v3, v1, v3, vcc
	v_lshl_add_u64 v[36:37], s[44:45], 0, v[28:29]
	v_lshlrev_b32_e32 v28, 2, v14
	s_addc_u32 s7, s87, s7
	v_lshlrev_b32_e32 v45, 2, v3
	v_xor_b32_e32 v3, 16, v1
	v_lshl_add_u64 v[38:39], s[44:45], 0, v[28:29]
	v_lshlrev_b32_e32 v28, 1, v0
	v_cmp_lt_i32_e32 vcc, v3, v2
	v_lshl_add_u64 v[16:17], s[6:7], 0, v[28:29]
	s_mov_b64 s[10:11], 0x3000000
	s_ashr_i32 s1, s0, 31
	s_ashr_i32 s5, s2, 31
	v_cndmask_b32_e32 v3, v1, v3, vcc
	v_lshl_add_u64 v[40:41], v[16:17], 0, s[10:11]
	s_add_u32 s10, s0, s2
	v_lshlrev_b32_e32 v46, 2, v3
	v_xor_b32_e32 v3, 32, v1
	s_addc_u32 s11, s1, s5
	v_cmp_lt_i32_e32 vcc, v3, v2
	s_ashr_i32 s5, s4, 31
	s_lshl_b64 s[0:1], s[10:11], 13
	v_cndmask_b32_e32 v1, v1, v3, vcc
	v_or_b32_e32 v2, 0x100, v0
	v_or_b32_e32 v4, 0x200, v0
	v_or_b32_e32 v6, 0x300, v0
	s_add_u32 s12, s36, s0
	s_mov_b32 s9, 0
	v_lshlrev_b32_e32 v47, 2, v1
	s_addc_u32 s13, s37, s1
	s_lshl_b64 s[14:15], s[4:5], 13
	v_lshlrev_b32_e32 v28, 2, v0
	s_movk_i32 s0, 0x1000
	v_mov_b32_e32 v48, 0x358637bd
	s_mov_b32 s1, 0x800000
	v_lshlrev_b32_e32 v49, 2, v2
	v_lshlrev_b32_e32 v50, 2, v4
	v_lshlrev_b32_e32 v51, 2, v6
	v_lshlrev_b32_e32 v52, 2, v8
	v_lshlrev_b32_e32 v53, 2, v10
	v_lshlrev_b32_e32 v54, 2, v12
	v_lshlrev_b32_e32 v55, 2, v14
	global_load_dwordx4 v[96:99], v[30:31], off
	global_load_dwordx4 v[100:103], v[30:31], off offset:1024
	global_load_dwordx4 v[104:107], v[30:31], off offset:2048
	global_load_dwordx4 v[108:111], v[30:31], off offset:3072
	global_load_dwordx4 v[112:115], v[32:33], off
	global_load_dwordx4 v[116:119], v[34:35], off
	global_load_dwordx4 v[120:123], v[36:37], off
	global_load_dwordx4 v[124:127], v[38:39], off
	s_cmp_lt_i32 s10, 0x8000
	s_mov_b64 s[18:19], s[10:11]
	s_mov_b64 s[16:17], s[12:13]
	s_cbranch_scc1 .Lp1_x1
	s_add_i32 s8, s10, 0xffff8000
	s_lshl_b64 s[16:17], s[8:9], 13
	s_add_u32 s16, s40, s16
	s_mov_b32 s8, s10
	s_addc_u32 s17, s41, s17
	s_mov_b64 s[18:19], s[8:9]
.Lp1_x1:
	global_load_dwordx4 v[56:59], v28, s[16:17] nt
	global_load_dwordx4 v[24:27], v28, s[16:17] offset:1024 nt
	global_load_dwordx4 v[20:23], v28, s[16:17] offset:2048 nt
	global_load_dwordx4 v[16:19], v28, s[16:17] offset:3072 nt
	global_load_dwordx4 v[12:15], v52, s[16:17] nt
	global_load_dwordx4 v[8:11], v52, s[16:17] offset:1024 nt
	global_load_dwordx4 v[4:7], v52, s[16:17] offset:2048 nt
	global_load_dwordx4 v[0:3], v52, s[16:17] offset:3072 nt
	s_min_i32 s2, s10, 0x8000
	s_ashr_i32 s2, s2, 13
	s_mul_i32 s16, s2, 0x1800
	s_ashr_i32 s17, s16, 31
	s_lshl_b64 s[16:17], s[16:17], 2
	s_add_u32 s16, s6, s16
	s_addc_u32 s17, s7, s17
	s_lshl_b64 s[20:21], s[18:19], 12
	s_add_u32 s18, s16, 0x2000
	s_addc_u32 s19, s17, 0
	global_load_dwordx4 v[128:131], v28, s[16:17]
	global_load_dwordx4 v[132:135], v28, s[16:17] offset:1024
	global_load_dwordx4 v[136:139], v28, s[16:17] offset:2048
	global_load_dwordx4 v[140:143], v28, s[16:17] offset:3072
	global_load_dwordx4 v[144:147], v52, s[16:17]
	global_load_dwordx4 v[148:151], v52, s[16:17] offset:1024
	global_load_dwordx4 v[152:155], v52, s[16:17] offset:2048
	global_load_dwordx4 v[156:159], v52, s[16:17] offset:3072
	global_load_dwordx4 v[160:163], v28, s[18:19]
	global_load_dwordx4 v[164:167], v28, s[18:19] offset:1024
	global_load_dwordx4 v[168:171], v28, s[18:19] offset:2048
	global_load_dwordx4 v[172:175], v28, s[18:19] offset:3072
	global_load_dwordx4 v[176:179], v52, s[18:19]
	global_load_dwordx4 v[180:183], v52, s[18:19] offset:1024
	global_load_dwordx4 v[184:187], v52, s[18:19] offset:2048
	global_load_dwordx4 v[188:191], v52, s[18:19] offset:3072
	s_add_u32 s10, s10, s4
	s_addc_u32 s11, s11, s5
	s_add_u32 s12, s12, s14
	s_addc_u32 s13, s13, s15
	s_waitcnt vmcnt(0)
.Lp1_A:
	s_cmp_gt_i32 s10, 0x83ff
	s_cbranch_scc1 .Lp1_lastA
	s_cmp_lt_i32 s10, 0x8000
	s_mov_b64 s[18:19], s[10:11]
	s_mov_b64 s[16:17], s[12:13]
	s_cbranch_scc1 .Lp1_x2
	s_add_i32 s8, s10, 0xffff8000
	s_lshl_b64 s[16:17], s[8:9], 13
	s_add_u32 s16, s40, s16
	s_mov_b32 s8, s10
	s_addc_u32 s17, s41, s17
	s_mov_b64 s[18:19], s[8:9]
; __device__ __forceinline__ unsigned cvtpk(float lo, float hi) { unsigned r; asm volatile("v_cvt_pk_bf16_f32 %0, %1, %2" : "=v"(r) : "v"(lo), "v"(hi)); return r; }
; __global__ void __launch_bounds__(512, 2) fwd_megakernel(Params p) {
;     ...
;             f32x4 v[8]; float ss = 0.f;
; #pragma unroll
;             for (int j = 0; j < 8; ++j) { v[j] = __builtin_nontemporal_load((const f32x4*)(src + j * 256 + lane * 4)); ss += (v[j].x * v[j].x + v[j].y * v[j].y) + (v[j].z * v[j].z + v[j].w * v[j].w); }
;             const float rstd = rsqrtf(wave_sum(ss) * (1.f / DM) + 1e-6f);
;             bf16_t* orow = HX + (size_t)R * DM;
; #pragma unroll
;             for (int j = 0; j < 8; ++j) { const int k = j * 256 + lane * 4;
;                 const f32x4 g4 = *(const f32x4*)(p.norm_g + k), sh = *(const f32x4*)(mr + k), sc4 = *(const f32x4*)(mr + 2048 + k);
;                 const f32x4 y = v[j] * rstd * g4 * (sc4 + 1.f) + sh;
;                 uint2 w; w.x = cvtpk(y.x, y.y); w.y = cvtpk(y.z, y.w); *(uint2*)(orow + k) = w; }
.Lp1_x2:
	global_load_dwordx4 v[202:205], v28, s[16:17] nt
	global_load_dwordx4 v[206:209], v28, s[16:17] offset:1024 nt
	global_load_dwordx4 v[210:213], v28, s[16:17] offset:2048 nt
	global_load_dwordx4 v[214:217], v28, s[16:17] offset:3072 nt
	global_load_dwordx4 v[218:221], v52, s[16:17] nt
	global_load_dwordx4 v[222:225], v52, s[16:17] offset:1024 nt
	global_load_dwordx4 v[232:235], v52, s[16:17] offset:2048 nt
	global_load_dwordx4 v[236:239], v52, s[16:17] offset:3072 nt
	s_waitcnt vmcnt(32)
	v_mul_f32_e32 v81, v57, v57
	v_mul_f32_e32 v82, v59, v59
	v_fmac_f32_e32 v81, v56, v56
	v_fmac_f32_e32 v82, v58, v58
	v_add_f32_e32 v80, v81, v82
	v_mul_f32_e32 v81, v25, v25
	v_mul_f32_e32 v82, v27, v27
	v_fmac_f32_e32 v81, v24, v24
	v_fmac_f32_e32 v82, v26, v26
	v_add_f32_e32 v81, v81, v82
	v_add_f32_e32 v80, v80, v81
	v_mul_f32_e32 v81, v21, v21
	v_mul_f32_e32 v82, v23, v23
	v_fmac_f32_e32 v81, v20, v20
	v_fmac_f32_e32 v82, v22, v22
	v_add_f32_e32 v81, v81, v82
	v_add_f32_e32 v80, v80, v81
	v_mul_f32_e32 v81, v17, v17
	v_mul_f32_e32 v82, v19, v19
	v_fmac_f32_e32 v81, v16, v16
	v_fmac_f32_e32 v82, v18, v18
	v_add_f32_e32 v81, v81, v82
	v_add_f32_e32 v80, v80, v81
	v_mul_f32_e32 v81, v13, v13
	v_mul_f32_e32 v82, v15, v15
	v_fmac_f32_e32 v81, v12, v12
	v_fmac_f32_e32 v82, v14, v14
	v_add_f32_e32 v81, v81, v82
	v_add_f32_e32 v80, v80, v81
	v_mul_f32_e32 v81, v9, v9
	v_mul_f32_e32 v82, v11, v11
	v_fmac_f32_e32 v81, v8, v8
	v_fmac_f32_e32 v82, v10, v10
	v_add_f32_e32 v81, v81, v82
	v_add_f32_e32 v80, v80, v81
	v_mul_f32_e32 v81, v5, v5
	v_mul_f32_e32 v82, v7, v7
	v_fmac_f32_e32 v81, v4, v4
	v_fmac_f32_e32 v82, v6, v6
	v_add_f32_e32 v81, v81, v82
	v_add_f32_e32 v80, v80, v81
	v_mul_f32_e32 v81, v1, v1
	v_mul_f32_e32 v82, v3, v3
	v_fmac_f32_e32 v81, v0, v0
	v_fmac_f32_e32 v82, v2, v2
	v_add_f32_e32 v81, v81, v82
	v_add_f32_e32 v80, v80, v81
	ds_bpermute_b32 v83, v42, v80
	s_waitcnt lgkmcnt(0)
	v_add_f32_e32 v80, v80, v83
	ds_bpermute_b32 v83, v43, v80
	s_waitcnt lgkmcnt(0)
	v_add_f32_e32 v80, v80, v83
	ds_bpermute_b32 v83, v44, v80
	s_waitcnt lgkmcnt(0)
	v_add_f32_e32 v80, v80, v83
	ds_bpermute_b32 v83, v45, v80
	s_waitcnt lgkmcnt(0)
	v_add_f32_e32 v80, v80, v83
	ds_bpermute_b32 v83, v46, v80
	s_waitcnt lgkmcnt(0)
	v_add_f32_e32 v80, v80, v83
	ds_bpermute_b32 v83, v47, v80
	s_waitcnt lgkmcnt(0)
	v_add_f32_e32 v80, v80, v83
	v_fmamk_f32 v80, v80, 0x3a000000, v48
	v_mul_f32_e32 v81, 0x4b800000, v80
	v_cmp_gt_f32_e32 vcc, s1, v80
	s_nop 1
	v_cndmask_b32_e32 v80, v80, v81, vcc
	v_rsq_f32_e32 v84, v80
	v_lshl_add_u64 v[92:93], v[40:41], 0, s[20:21]
	s_nop 0
	v_mul_f32_e32 v85, 0x45800000, v84
	s_nop 0
	v_cndmask_b32_e32 v84, v84, v85, vcc
	s_waitcnt vmcnt(16)
	v_pk_mul_f32 v[56:57], v[84:85], v[56:57] op_sel_hi:[0,1]
	v_pk_add_f32 v[160:161], v[160:161], 1.0 op_sel_hi:[1,0]
	v_pk_mul_f32 v[56:57], v[56:57], v[96:97]
	v_pk_fma_f32 v[56:57], v[56:57], v[160:161], v[128:129]
	v_pk_mul_f32 v[58:59], v[84:85], v[58:59] op_sel_hi:[0,1]
	v_pk_add_f32 v[162:163], v[162:163], 1.0 op_sel_hi:[1,0]
	v_pk_mul_f32 v[58:59], v[58:59], v[98:99]
	v_pk_fma_f32 v[58:59], v[58:59], v[162:163], v[130:131]
	v_cvt_pk_bf16_f32 v64, v56, v57
	v_cvt_pk_bf16_f32 v65, v58, v59
	v_pk_mul_f32 v[24:25], v[84:85], v[24:25] op_sel_hi:[0,1]
	v_pk_add_f32 v[164:165], v[164:165], 1.0 op_sel_hi:[1,0]
	v_pk_mul_f32 v[24:25], v[24:25], v[100:101]
	v_pk_fma_f32 v[24:25], v[24:25], v[164:165], v[132:133]
	v_pk_mul_f32 v[26:27], v[84:85], v[26:27] op_sel_hi:[0,1]
	v_pk_add_f32 v[166:167], v[166:167], 1.0 op_sel_hi:[1,0]
	v_pk_mul_f32 v[26:27], v[26:27], v[102:103]
	v_pk_fma_f32 v[26:27], v[26:27], v[166:167], v[134:135]
	v_cvt_pk_bf16_f32 v66, v24, v25
	v_cvt_pk_bf16_f32 v67, v26, v27
	v_pk_mul_f32 v[20:21], v[84:85], v[20:21] op_sel_hi:[0,1]
	v_pk_add_f32 v[168:169], v[168:169], 1.0 op_sel_hi:[1,0]
	v_pk_mul_f32 v[20:21], v[20:21], v[104:105]
	v_pk_fma_f32 v[20:21], v[20:21], v[168:169], v[136:137]
	v_pk_mul_f32 v[22:23], v[84:85], v[22:23] op_sel_hi:[0,1]
	v_pk_add_f32 v[170:171], v[170:171], 1.0 op_sel_hi:[1,0]
	v_pk_mul_f32 v[22:23], v[22:23], v[106:107]
	v_pk_fma_f32 v[22:23], v[22:23], v[170:171], v[138:139]
	v_cvt_pk_bf16_f32 v68, v20, v21
	v_cvt_pk_bf16_f32 v69, v22, v23
	v_pk_mul_f32 v[16:17], v[84:85], v[16:17] op_sel_hi:[0,1]
	v_pk_add_f32 v[172:173], v[172:173], 1.0 op_sel_hi:[1,0]
	v_pk_mul_f32 v[16:17], v[16:17], v[108:109]
	v_pk_fma_f32 v[16:17], v[16:17], v[172:173], v[140:141]
	v_pk_mul_f32 v[18:19], v[84:85], v[18:19] op_sel_hi:[0,1]
	v_pk_add_f32 v[174:175], v[174:175], 1.0 op_sel_hi:[1,0]
	v_pk_mul_f32 v[18:19], v[18:19], v[110:111]
	v_pk_fma_f32 v[18:19], v[18:19], v[174:175], v[142:143]
	v_cvt_pk_bf16_f32 v70, v16, v17
	v_cvt_pk_bf16_f32 v71, v18, v19
	v_pk_mul_f32 v[12:13], v[84:85], v[12:13] op_sel_hi:[0,1]
	v_pk_add_f32 v[176:177], v[176:177], 1.0 op_sel_hi:[1,0]
	v_pk_mul_f32 v[12:13], v[12:13], v[112:113]
	v_pk_fma_f32 v[12:13], v[12:13], v[176:177], v[144:145]
	v_pk_mul_f32 v[14:15], v[84:85], v[14:15] op_sel_hi:[0,1]
	v_pk_add_f32 v[178:179], v[178:179], 1.0 op_sel_hi:[1,0]
	v_pk_mul_f32 v[14:15], v[14:15], v[114:115]
	v_pk_fma_f32 v[14:15], v[14:15], v[178:179], v[146:147]
	v_cvt_pk_bf16_f32 v72, v12, v13
	v_cvt_pk_bf16_f32 v73, v14, v15
	v_pk_mul_f32 v[8:9], v[84:85], v[8:9] op_sel_hi:[0,1]
	v_pk_add_f32 v[180:181], v[180:181], 1.0 op_sel_hi:[1,0]
	v_pk_mul_f32 v[8:9], v[8:9], v[116:117]
	v_pk_fma_f32 v[8:9], v[8:9], v[180:181], v[148:149]
	v_pk_mul_f32 v[10:11], v[84:85], v[10:11] op_sel_hi:[0,1]
	v_pk_add_f32 v[182:183], v[182:183], 1.0 op_sel_hi:[1,0]
	v_pk_mul_f32 v[10:11], v[10:11], v[118:119]
	v_pk_fma_f32 v[10:11], v[10:11], v[182:183], v[150:151]
; __device__ __forceinline__ unsigned cvtpk(float lo, float hi) { unsigned r; asm volatile("v_cvt_pk_bf16_f32 %0, %1, %2" : "=v"(r) : "v"(lo), "v"(hi)); return r; }
; __global__ void __launch_bounds__(512, 2) fwd_megakernel(Params p) {
;     ...
;             f32x4 v[8]; float ss = 0.f;
; #pragma unroll
;             for (int j = 0; j < 8; ++j) { v[j] = __builtin_nontemporal_load((const f32x4*)(src + j * 256 + lane * 4)); ss += (v[j].x * v[j].x + v[j].y * v[j].y) + (v[j].z * v[j].z + v[j].w * v[j].w); }
;             const float rstd = rsqrtf(wave_sum(ss) * (1.f / DM) + 1e-6f);
;             bf16_t* orow = HX + (size_t)R * DM;
; #pragma unroll
;             for (int j = 0; j < 8; ++j) { const int k = j * 256 + lane * 4;
;                 const f32x4 g4 = *(const f32x4*)(p.norm_g + k), sh = *(const f32x4*)(mr + k), sc4 = *(const f32x4*)(mr + 2048 + k);
;                 const f32x4 y = v[j] * rstd * g4 * (sc4 + 1.f) + sh;
;                 uint2 w; w.x = cvtpk(y.x, y.y); w.y = cvtpk(y.z, y.w); *(uint2*)(orow + k) = w; }
	v_cvt_pk_bf16_f32 v74, v8, v9
	v_cvt_pk_bf16_f32 v75, v10, v11
	v_pk_mul_f32 v[4:5], v[84:85], v[4:5] op_sel_hi:[0,1]
	v_pk_add_f32 v[184:185], v[184:185], 1.0 op_sel_hi:[1,0]
	v_pk_mul_f32 v[4:5], v[4:5], v[120:121]
	v_pk_fma_f32 v[4:5], v[4:5], v[184:185], v[152:153]
	v_pk_mul_f32 v[6:7], v[84:85], v[6:7] op_sel_hi:[0,1]
	v_pk_add_f32 v[186:187], v[186:187], 1.0 op_sel_hi:[1,0]
	v_pk_mul_f32 v[6:7], v[6:7], v[122:123]
	v_pk_fma_f32 v[6:7], v[6:7], v[186:187], v[154:155]
	v_cvt_pk_bf16_f32 v76, v4, v5
	v_cvt_pk_bf16_f32 v77, v6, v7
	v_pk_mul_f32 v[0:1], v[84:85], v[0:1] op_sel_hi:[0,1]
	v_pk_add_f32 v[188:189], v[188:189], 1.0 op_sel_hi:[1,0]
	v_pk_mul_f32 v[0:1], v[0:1], v[124:125]
	v_pk_fma_f32 v[0:1], v[0:1], v[188:189], v[156:157]
	v_pk_mul_f32 v[2:3], v[84:85], v[2:3] op_sel_hi:[0,1]
	v_pk_add_f32 v[190:191], v[190:191], 1.0 op_sel_hi:[1,0]
	v_pk_mul_f32 v[2:3], v[2:3], v[126:127]
	v_pk_fma_f32 v[2:3], v[2:3], v[190:191], v[158:159]
	v_cvt_pk_bf16_f32 v78, v0, v1
	v_cvt_pk_bf16_f32 v79, v2, v3
	s_min_i32 s2, s10, 0x8000
	s_ashr_i32 s2, s2, 13
	s_mul_i32 s16, s2, 0x1800
	s_ashr_i32 s17, s16, 31
	s_lshl_b64 s[16:17], s[16:17], 2
	s_add_u32 s16, s6, s16
	s_addc_u32 s17, s7, s17
	s_lshl_b64 s[20:21], s[18:19], 12
	s_add_u32 s18, s16, 0x2000
	s_addc_u32 s19, s17, 0
	global_load_dwordx4 v[128:131], v28, s[16:17]
	global_load_dwordx4 v[132:135], v28, s[16:17] offset:1024
	global_load_dwordx4 v[136:139], v28, s[16:17] offset:2048
	global_load_dwordx4 v[140:143], v28, s[16:17] offset:3072
	global_load_dwordx4 v[144:147], v52, s[16:17]
	global_load_dwordx4 v[148:151], v52, s[16:17] offset:1024
	global_load_dwordx4 v[152:155], v52, s[16:17] offset:2048
	global_load_dwordx4 v[156:159], v52, s[16:17] offset:3072
	global_load_dwordx4 v[160:163], v28, s[18:19]
	global_load_dwordx4 v[164:167], v28, s[18:19] offset:1024
	global_load_dwordx4 v[168:171], v28, s[18:19] offset:2048
	global_load_dwordx4 v[172:175], v28, s[18:19] offset:3072
	global_load_dwordx4 v[176:179], v52, s[18:19]
	global_load_dwordx4 v[180:183], v52, s[18:19] offset:1024
	global_load_dwordx4 v[184:187], v52, s[18:19] offset:2048
	global_load_dwordx4 v[188:191], v52, s[18:19] offset:3072
	s_add_u32 s10, s10, s4
	s_addc_u32 s11, s11, s5
	s_add_u32 s12, s12, s14
	s_addc_u32 s13, s13, s15
	global_store_dwordx2 v[92:93], v[64:65], off
	global_store_dwordx2 v[92:93], v[66:67], off offset:512
	global_store_dwordx2 v[92:93], v[68:69], off offset:1024
	global_store_dwordx2 v[92:93], v[70:71], off offset:1536
	global_store_dwordx2 v[92:93], v[72:73], off offset:2048
	global_store_dwordx2 v[92:93], v[74:75], off offset:2560
	global_store_dwordx2 v[92:93], v[76:77], off offset:3072
	global_store_dwordx2 v[92:93], v[78:79], off offset:3584
	s_cmp_gt_i32 s10, 0x83ff
	s_cbranch_scc1 .Lp1_lastB
	s_cmp_lt_i32 s10, 0x8000
	s_mov_b64 s[18:19], s[10:11]
	s_mov_b64 s[16:17], s[12:13]
	s_cbranch_scc1 .Lp1_x3
	s_add_i32 s8, s10, 0xffff8000
	s_lshl_b64 s[16:17], s[8:9], 13
	s_add_u32 s16, s40, s16
	s_mov_b32 s8, s10
	s_addc_u32 s17, s41, s17
	s_mov_b64 s[18:19], s[8:9]
.Lp1_x3:
	global_load_dwordx4 v[56:59], v28, s[16:17] nt
	global_load_dwordx4 v[24:27], v28, s[16:17] offset:1024 nt
	global_load_dwordx4 v[20:23], v28, s[16:17] offset:2048 nt
	global_load_dwordx4 v[16:19], v28, s[16:17] offset:3072 nt
	global_load_dwordx4 v[12:15], v52, s[16:17] nt
	global_load_dwordx4 v[8:11], v52, s[16:17] offset:1024 nt
	global_load_dwordx4 v[4:7], v52, s[16:17] offset:2048 nt
	global_load_dwordx4 v[0:3], v52, s[16:17] offset:3072 nt
	s_waitcnt vmcnt(32)
	v_mul_f32_e32 v81, v203, v203
	v_mul_f32_e32 v82, v205, v205
	v_fmac_f32_e32 v81, v202, v202
	v_fmac_f32_e32 v82, v204, v204
	v_add_f32_e32 v80, v81, v82
	v_mul_f32_e32 v81, v207, v207
	v_mul_f32_e32 v82, v209, v209
	v_fmac_f32_e32 v81, v206, v206
	v_fmac_f32_e32 v82, v208, v208
	v_add_f32_e32 v81, v81, v82
	v_add_f32_e32 v80, v80, v81
	v_mul_f32_e32 v81, v211, v211
	v_mul_f32_e32 v82, v213, v213
	v_fmac_f32_e32 v81, v210, v210
	v_fmac_f32_e32 v82, v212, v212
	v_add_f32_e32 v81, v81, v82
	v_add_f32_e32 v80, v80, v81
	v_mul_f32_e32 v81, v215, v215
	v_mul_f32_e32 v82, v217, v217
	v_fmac_f32_e32 v81, v214, v214
	v_fmac_f32_e32 v82, v216, v216
	v_add_f32_e32 v81, v81, v82
	v_add_f32_e32 v80, v80, v81
	v_mul_f32_e32 v81, v219, v219
	v_mul_f32_e32 v82, v221, v221
	v_fmac_f32_e32 v81, v218, v218
	v_fmac_f32_e32 v82, v220, v220
	v_add_f32_e32 v81, v81, v82
	v_add_f32_e32 v80, v80, v81
	v_mul_f32_e32 v81, v223, v223
	v_mul_f32_e32 v82, v225, v225
	v_fmac_f32_e32 v81, v222, v222
	v_fmac_f32_e32 v82, v224, v224
	v_add_f32_e32 v81, v81, v82
	v_add_f32_e32 v80, v80, v81
	v_mul_f32_e32 v81, v233, v233
	v_mul_f32_e32 v82, v235, v235
	v_fmac_f32_e32 v81, v232, v232
	v_fmac_f32_e32 v82, v234, v234
	v_add_f32_e32 v81, v81, v82
	v_add_f32_e32 v80, v80, v81
	v_mul_f32_e32 v81, v237, v237
	v_mul_f32_e32 v82, v239, v239
	v_fmac_f32_e32 v81, v236, v236
	v_fmac_f32_e32 v82, v238, v238
	v_add_f32_e32 v81, v81, v82
	v_add_f32_e32 v80, v80, v81
	ds_bpermute_b32 v83, v42, v80
	s_waitcnt lgkmcnt(0)
	v_add_f32_e32 v80, v80, v83
	ds_bpermute_b32 v83, v43, v80
	s_waitcnt lgkmcnt(0)
	v_add_f32_e32 v80, v80, v83
	ds_bpermute_b32 v83, v44, v80
	s_waitcnt lgkmcnt(0)
	v_add_f32_e32 v80, v80, v83
	ds_bpermute_b32 v83, v45, v80
	s_waitcnt lgkmcnt(0)
	v_add_f32_e32 v80, v80, v83
	ds_bpermute_b32 v83, v46, v80
	s_waitcnt lgkmcnt(0)
	v_add_f32_e32 v80, v80, v83
	ds_bpermute_b32 v83, v47, v80
	s_waitcnt lgkmcnt(0)
	v_add_f32_e32 v80, v80, v83
	v_fmamk_f32 v80, v80, 0x3a000000, v48
	v_mul_f32_e32 v81, 0x4b800000, v80
	v_cmp_gt_f32_e32 vcc, s1, v80
	s_nop 1
	v_cndmask_b32_e32 v80, v80, v81, vcc
	v_rsq_f32_e32 v84, v80
	v_lshl_add_u64 v[92:93], v[40:41], 0, s[20:21]
	s_nop 0
	v_mul_f32_e32 v85, 0x45800000, v84
	s_nop 0
	v_cndmask_b32_e32 v84, v84, v85, vcc
	s_waitcnt vmcnt(16)
; __device__ __forceinline__ unsigned cvtpk(float lo, float hi) { unsigned r; asm volatile("v_cvt_pk_bf16_f32 %0, %1, %2" : "=v"(r) : "v"(lo), "v"(hi)); return r; }
; __global__ void __launch_bounds__(512, 2) fwd_megakernel(Params p) {
;     ...
;             f32x4 v[8]; float ss = 0.f;
; #pragma unroll
;             for (int j = 0; j < 8; ++j) { v[j] = __builtin_nontemporal_load((const f32x4*)(src + j * 256 + lane * 4)); ss += (v[j].x * v[j].x + v[j].y * v[j].y) + (v[j].z * v[j].z + v[j].w * v[j].w); }
;             const float rstd = rsqrtf(wave_sum(ss) * (1.f / DM) + 1e-6f);
;             bf16_t* orow = HX + (size_t)R * DM;
; #pragma unroll
;             for (int j = 0; j < 8; ++j) { const int k = j * 256 + lane * 4;
;                 const f32x4 g4 = *(const f32x4*)(p.norm_g + k), sh = *(const f32x4*)(mr + k), sc4 = *(const f32x4*)(mr + 2048 + k);
;                 const f32x4 y = v[j] * rstd * g4 * (sc4 + 1.f) + sh;
;                 uint2 w; w.x = cvtpk(y.x, y.y); w.y = cvtpk(y.z, y.w); *(uint2*)(orow + k) = w; }
	v_pk_mul_f32 v[202:203], v[84:85], v[202:203] op_sel_hi:[0,1]
	v_pk_add_f32 v[160:161], v[160:161], 1.0 op_sel_hi:[1,0]
	v_pk_mul_f32 v[202:203], v[202:203], v[96:97]
	v_pk_fma_f32 v[202:203], v[202:203], v[160:161], v[128:129]
	v_pk_mul_f32 v[204:205], v[84:85], v[204:205] op_sel_hi:[0,1]
	v_pk_add_f32 v[162:163], v[162:163], 1.0 op_sel_hi:[1,0]
	v_pk_mul_f32 v[204:205], v[204:205], v[98:99]
	v_pk_fma_f32 v[204:205], v[204:205], v[162:163], v[130:131]
	v_cvt_pk_bf16_f32 v64, v202, v203
	v_cvt_pk_bf16_f32 v65, v204, v205
	v_pk_mul_f32 v[206:207], v[84:85], v[206:207] op_sel_hi:[0,1]
	v_pk_add_f32 v[164:165], v[164:165], 1.0 op_sel_hi:[1,0]
	v_pk_mul_f32 v[206:207], v[206:207], v[100:101]
	v_pk_fma_f32 v[206:207], v[206:207], v[164:165], v[132:133]
	v_pk_mul_f32 v[208:209], v[84:85], v[208:209] op_sel_hi:[0,1]
	v_pk_add_f32 v[166:167], v[166:167], 1.0 op_sel_hi:[1,0]
	v_pk_mul_f32 v[208:209], v[208:209], v[102:103]
	v_pk_fma_f32 v[208:209], v[208:209], v[166:167], v[134:135]
	v_cvt_pk_bf16_f32 v66, v206, v207
	v_cvt_pk_bf16_f32 v67, v208, v209
	v_pk_mul_f32 v[210:211], v[84:85], v[210:211] op_sel_hi:[0,1]
	v_pk_add_f32 v[168:169], v[168:169], 1.0 op_sel_hi:[1,0]
	v_pk_mul_f32 v[210:211], v[210:211], v[104:105]
	v_pk_fma_f32 v[210:211], v[210:211], v[168:169], v[136:137]
	v_pk_mul_f32 v[212:213], v[84:85], v[212:213] op_sel_hi:[0,1]
	v_pk_add_f32 v[170:171], v[170:171], 1.0 op_sel_hi:[1,0]
	v_pk_mul_f32 v[212:213], v[212:213], v[106:107]
	v_pk_fma_f32 v[212:213], v[212:213], v[170:171], v[138:139]
	v_cvt_pk_bf16_f32 v68, v210, v211
	v_cvt_pk_bf16_f32 v69, v212, v213
	v_pk_mul_f32 v[214:215], v[84:85], v[214:215] op_sel_hi:[0,1]
	v_pk_add_f32 v[172:173], v[172:173], 1.0 op_sel_hi:[1,0]
	v_pk_mul_f32 v[214:215], v[214:215], v[108:109]
	v_pk_fma_f32 v[214:215], v[214:215], v[172:173], v[140:141]
	v_pk_mul_f32 v[216:217], v[84:85], v[216:217] op_sel_hi:[0,1]
	v_pk_add_f32 v[174:175], v[174:175], 1.0 op_sel_hi:[1,0]
	v_pk_mul_f32 v[216:217], v[216:217], v[110:111]
	v_pk_fma_f32 v[216:217], v[216:217], v[174:175], v[142:143]
	v_cvt_pk_bf16_f32 v70, v214, v215
	v_cvt_pk_bf16_f32 v71, v216, v217
	v_pk_mul_f32 v[218:219], v[84:85], v[218:219] op_sel_hi:[0,1]
	v_pk_add_f32 v[176:177], v[176:177], 1.0 op_sel_hi:[1,0]
	v_pk_mul_f32 v[218:219], v[218:219], v[112:113]
	v_pk_fma_f32 v[218:219], v[218:219], v[176:177], v[144:145]
	v_pk_mul_f32 v[220:221], v[84:85], v[220:221] op_sel_hi:[0,1]
	v_pk_add_f32 v[178:179], v[178:179], 1.0 op_sel_hi:[1,0]
	v_pk_mul_f32 v[220:221], v[220:221], v[114:115]
	v_pk_fma_f32 v[220:221], v[220:221], v[178:179], v[146:147]
	v_cvt_pk_bf16_f32 v72, v218, v219
	v_cvt_pk_bf16_f32 v73, v220, v221
	v_pk_mul_f32 v[222:223], v[84:85], v[222:223] op_sel_hi:[0,1]
	v_pk_add_f32 v[180:181], v[180:181], 1.0 op_sel_hi:[1,0]
	v_pk_mul_f32 v[222:223], v[222:223], v[116:117]
	v_pk_fma_f32 v[222:223], v[222:223], v[180:181], v[148:149]
	v_pk_mul_f32 v[224:225], v[84:85], v[224:225] op_sel_hi:[0,1]
	v_pk_add_f32 v[182:183], v[182:183], 1.0 op_sel_hi:[1,0]
	v_pk_mul_f32 v[224:225], v[224:225], v[118:119]
	v_pk_fma_f32 v[224:225], v[224:225], v[182:183], v[150:151]
	v_cvt_pk_bf16_f32 v74, v222, v223
	v_cvt_pk_bf16_f32 v75, v224, v225
	v_pk_mul_f32 v[232:233], v[84:85], v[232:233] op_sel_hi:[0,1]
	v_pk_add_f32 v[184:185], v[184:185], 1.0 op_sel_hi:[1,0]
	v_pk_mul_f32 v[232:233], v[232:233], v[120:121]
	v_pk_fma_f32 v[232:233], v[232:233], v[184:185], v[152:153]
	v_pk_mul_f32 v[234:235], v[84:85], v[234:235] op_sel_hi:[0,1]
	v_pk_add_f32 v[186:187], v[186:187], 1.0 op_sel_hi:[1,0]
	v_pk_mul_f32 v[234:235], v[234:235], v[122:123]
	v_pk_fma_f32 v[234:235], v[234:235], v[186:187], v[154:155]
	v_cvt_pk_bf16_f32 v76, v232, v233
	v_cvt_pk_bf16_f32 v77, v234, v235
	v_pk_mul_f32 v[236:237], v[84:85], v[236:237] op_sel_hi:[0,1]
	v_pk_add_f32 v[188:189], v[188:189], 1.0 op_sel_hi:[1,0]
	v_pk_mul_f32 v[236:237], v[236:237], v[124:125]
	v_pk_fma_f32 v[236:237], v[236:237], v[188:189], v[156:157]
	v_pk_mul_f32 v[238:239], v[84:85], v[238:239] op_sel_hi:[0,1]
	v_pk_add_f32 v[190:191], v[190:191], 1.0 op_sel_hi:[1,0]
	v_pk_mul_f32 v[238:239], v[238:239], v[126:127]
	v_pk_fma_f32 v[238:239], v[238:239], v[190:191], v[158:159]
	v_cvt_pk_bf16_f32 v78, v236, v237
	v_cvt_pk_bf16_f32 v79, v238, v239
	s_min_i32 s2, s10, 0x8000
	s_ashr_i32 s2, s2, 13
	s_mul_i32 s16, s2, 0x1800
	s_ashr_i32 s17, s16, 31
	s_lshl_b64 s[16:17], s[16:17], 2
	s_add_u32 s16, s6, s16
	s_addc_u32 s17, s7, s17
	s_lshl_b64 s[20:21], s[18:19], 12
	s_add_u32 s18, s16, 0x2000
	s_addc_u32 s19, s17, 0
	global_load_dwordx4 v[128:131], v28, s[16:17]
	global_load_dwordx4 v[132:135], v28, s[16:17] offset:1024
	global_load_dwordx4 v[136:139], v28, s[16:17] offset:2048
	global_load_dwordx4 v[140:143], v28, s[16:17] offset:3072
	global_load_dwordx4 v[144:147], v52, s[16:17]
	global_load_dwordx4 v[148:151], v52, s[16:17] offset:1024
	global_load_dwordx4 v[152:155], v52, s[16:17] offset:2048
	global_load_dwordx4 v[156:159], v52, s[16:17] offset:3072
	global_load_dwordx4 v[160:163], v28, s[18:19]
	global_load_dwordx4 v[164:167], v28, s[18:19] offset:1024
	global_load_dwordx4 v[168:171], v28, s[18:19] offset:2048
	global_load_dwordx4 v[172:175], v28, s[18:19] offset:3072
	global_load_dwordx4 v[176:179], v52, s[18:19]
	global_load_dwordx4 v[180:183], v52, s[18:19] offset:1024
	global_load_dwordx4 v[184:187], v52, s[18:19] offset:2048
	global_load_dwordx4 v[188:191], v52, s[18:19] offset:3072
	s_add_u32 s10, s10, s4
	s_addc_u32 s11, s11, s5
	s_add_u32 s12, s12, s14
	s_addc_u32 s13, s13, s15
	global_store_dwordx2 v[92:93], v[64:65], off
	global_store_dwordx2 v[92:93], v[66:67], off offset:512
	global_store_dwordx2 v[92:93], v[68:69], off offset:1024
	global_store_dwordx2 v[92:93], v[70:71], off offset:1536
	global_store_dwordx2 v[92:93], v[72:73], off offset:2048
	global_store_dwordx2 v[92:93], v[74:75], off offset:2560
	global_store_dwordx2 v[92:93], v[76:77], off offset:3072
	global_store_dwordx2 v[92:93], v[78:79], off offset:3584
	s_branch .Lp1_A
; __device__ __forceinline__ unsigned cvtpk(float lo, float hi) { unsigned r; asm volatile("v_cvt_pk_bf16_f32 %0, %1, %2" : "=v"(r) : "v"(lo), "v"(hi)); return r; }
; __global__ void __launch_bounds__(512, 2) fwd_megakernel(Params p) {
;     ...
;             f32x4 v[8]; float ss = 0.f;
; #pragma unroll
;             for (int j = 0; j < 8; ++j) { v[j] = __builtin_nontemporal_load((const f32x4*)(src + j * 256 + lane * 4)); ss += (v[j].x * v[j].x + v[j].y * v[j].y) + (v[j].z * v[j].z + v[j].w * v[j].w); }
;             const float rstd = rsqrtf(wave_sum(ss) * (1.f / DM) + 1e-6f);
;             bf16_t* orow = HX + (size_t)R * DM;
; #pragma unroll
;             for (int j = 0; j < 8; ++j) { const int k = j * 256 + lane * 4;
;                 const f32x4 g4 = *(const f32x4*)(p.norm_g + k), sh = *(const f32x4*)(mr + k), sc4 = *(const f32x4*)(mr + 2048 + k);
;                 const f32x4 y = v[j] * rstd * g4 * (sc4 + 1.f) + sh;
;                 uint2 w; w.x = cvtpk(y.x, y.y); w.y = cvtpk(y.z, y.w); *(uint2*)(orow + k) = w; }
.Lp1_lastA:
	s_waitcnt vmcnt(24)
	v_mul_f32_e32 v81, v57, v57
	v_mul_f32_e32 v82, v59, v59
	v_fmac_f32_e32 v81, v56, v56
	v_fmac_f32_e32 v82, v58, v58
	v_add_f32_e32 v80, v81, v82
	v_mul_f32_e32 v81, v25, v25
	v_mul_f32_e32 v82, v27, v27
	v_fmac_f32_e32 v81, v24, v24
	v_fmac_f32_e32 v82, v26, v26
	v_add_f32_e32 v81, v81, v82
	v_add_f32_e32 v80, v80, v81
	v_mul_f32_e32 v81, v21, v21
	v_mul_f32_e32 v82, v23, v23
	v_fmac_f32_e32 v81, v20, v20
	v_fmac_f32_e32 v82, v22, v22
	v_add_f32_e32 v81, v81, v82
	v_add_f32_e32 v80, v80, v81
	v_mul_f32_e32 v81, v17, v17
	v_mul_f32_e32 v82, v19, v19
	v_fmac_f32_e32 v81, v16, v16
	v_fmac_f32_e32 v82, v18, v18
	v_add_f32_e32 v81, v81, v82
	v_add_f32_e32 v80, v80, v81
	v_mul_f32_e32 v81, v13, v13
	v_mul_f32_e32 v82, v15, v15
	v_fmac_f32_e32 v81, v12, v12
	v_fmac_f32_e32 v82, v14, v14
	v_add_f32_e32 v81, v81, v82
	v_add_f32_e32 v80, v80, v81
	v_mul_f32_e32 v81, v9, v9
	v_mul_f32_e32 v82, v11, v11
	v_fmac_f32_e32 v81, v8, v8
	v_fmac_f32_e32 v82, v10, v10
	v_add_f32_e32 v81, v81, v82
	v_add_f32_e32 v80, v80, v81
	v_mul_f32_e32 v81, v5, v5
	v_mul_f32_e32 v82, v7, v7
	v_fmac_f32_e32 v81, v4, v4
	v_fmac_f32_e32 v82, v6, v6
	v_add_f32_e32 v81, v81, v82
	v_add_f32_e32 v80, v80, v81
	v_mul_f32_e32 v81, v1, v1
	v_mul_f32_e32 v82, v3, v3
	v_fmac_f32_e32 v81, v0, v0
	v_fmac_f32_e32 v82, v2, v2
	v_add_f32_e32 v81, v81, v82
	v_add_f32_e32 v80, v80, v81
	ds_bpermute_b32 v83, v42, v80
	s_waitcnt lgkmcnt(0)
	v_add_f32_e32 v80, v80, v83
	ds_bpermute_b32 v83, v43, v80
	s_waitcnt lgkmcnt(0)
	v_add_f32_e32 v80, v80, v83
	ds_bpermute_b32 v83, v44, v80
	s_waitcnt lgkmcnt(0)
	v_add_f32_e32 v80, v80, v83
	ds_bpermute_b32 v83, v45, v80
	s_waitcnt lgkmcnt(0)
	v_add_f32_e32 v80, v80, v83
	ds_bpermute_b32 v83, v46, v80
	s_waitcnt lgkmcnt(0)
	v_add_f32_e32 v80, v80, v83
	ds_bpermute_b32 v83, v47, v80
	s_waitcnt lgkmcnt(0)
	v_add_f32_e32 v80, v80, v83
	v_fmamk_f32 v80, v80, 0x3a000000, v48
	v_mul_f32_e32 v81, 0x4b800000, v80
	v_cmp_gt_f32_e32 vcc, s1, v80
	s_nop 1
	v_cndmask_b32_e32 v80, v80, v81, vcc
	v_rsq_f32_e32 v84, v80
	v_lshl_add_u64 v[92:93], v[40:41], 0, s[20:21]
	s_nop 0
	v_mul_f32_e32 v85, 0x45800000, v84
	s_nop 0
	v_cndmask_b32_e32 v84, v84, v85, vcc
	s_waitcnt vmcnt(8)
	v_pk_mul_f32 v[56:57], v[84:85], v[56:57] op_sel_hi:[0,1]
	v_pk_add_f32 v[160:161], v[160:161], 1.0 op_sel_hi:[1,0]
	v_pk_mul_f32 v[56:57], v[56:57], v[96:97]
	v_pk_fma_f32 v[56:57], v[56:57], v[160:161], v[128:129]
	v_pk_mul_f32 v[58:59], v[84:85], v[58:59] op_sel_hi:[0,1]
	v_pk_add_f32 v[162:163], v[162:163], 1.0 op_sel_hi:[1,0]
	v_pk_mul_f32 v[58:59], v[58:59], v[98:99]
	v_pk_fma_f32 v[58:59], v[58:59], v[162:163], v[130:131]
	v_cvt_pk_bf16_f32 v64, v56, v57
	v_cvt_pk_bf16_f32 v65, v58, v59
	v_pk_mul_f32 v[24:25], v[84:85], v[24:25] op_sel_hi:[0,1]
	v_pk_add_f32 v[164:165], v[164:165], 1.0 op_sel_hi:[1,0]
	v_pk_mul_f32 v[24:25], v[24:25], v[100:101]
	v_pk_fma_f32 v[24:25], v[24:25], v[164:165], v[132:133]
	v_pk_mul_f32 v[26:27], v[84:85], v[26:27] op_sel_hi:[0,1]
	v_pk_add_f32 v[166:167], v[166:167], 1.0 op_sel_hi:[1,0]
	v_pk_mul_f32 v[26:27], v[26:27], v[102:103]
	v_pk_fma_f32 v[26:27], v[26:27], v[166:167], v[134:135]
	v_cvt_pk_bf16_f32 v66, v24, v25
	v_cvt_pk_bf16_f32 v67, v26, v27
	v_pk_mul_f32 v[20:21], v[84:85], v[20:21] op_sel_hi:[0,1]
	v_pk_add_f32 v[168:169], v[168:169], 1.0 op_sel_hi:[1,0]
	v_pk_mul_f32 v[20:21], v[20:21], v[104:105]
	v_pk_fma_f32 v[20:21], v[20:21], v[168:169], v[136:137]
	v_pk_mul_f32 v[22:23], v[84:85], v[22:23] op_sel_hi:[0,1]
	v_pk_add_f32 v[170:171], v[170:171], 1.0 op_sel_hi:[1,0]
	v_pk_mul_f32 v[22:23], v[22:23], v[106:107]
	v_pk_fma_f32 v[22:23], v[22:23], v[170:171], v[138:139]
	v_cvt_pk_bf16_f32 v68, v20, v21
	v_cvt_pk_bf16_f32 v69, v22, v23
	v_pk_mul_f32 v[16:17], v[84:85], v[16:17] op_sel_hi:[0,1]
	v_pk_add_f32 v[172:173], v[172:173], 1.0 op_sel_hi:[1,0]
	v_pk_mul_f32 v[16:17], v[16:17], v[108:109]
	v_pk_fma_f32 v[16:17], v[16:17], v[172:173], v[140:141]
	v_pk_mul_f32 v[18:19], v[84:85], v[18:19] op_sel_hi:[0,1]
	v_pk_add_f32 v[174:175], v[174:175], 1.0 op_sel_hi:[1,0]
	v_pk_mul_f32 v[18:19], v[18:19], v[110:111]
	v_pk_fma_f32 v[18:19], v[18:19], v[174:175], v[142:143]
	v_cvt_pk_bf16_f32 v70, v16, v17
	v_cvt_pk_bf16_f32 v71, v18, v19
	v_pk_mul_f32 v[12:13], v[84:85], v[12:13] op_sel_hi:[0,1]
	v_pk_add_f32 v[176:177], v[176:177], 1.0 op_sel_hi:[1,0]
	v_pk_mul_f32 v[12:13], v[12:13], v[112:113]
	v_pk_fma_f32 v[12:13], v[12:13], v[176:177], v[144:145]
	v_pk_mul_f32 v[14:15], v[84:85], v[14:15] op_sel_hi:[0,1]
	v_pk_add_f32 v[178:179], v[178:179], 1.0 op_sel_hi:[1,0]
	v_pk_mul_f32 v[14:15], v[14:15], v[114:115]
	v_pk_fma_f32 v[14:15], v[14:15], v[178:179], v[146:147]
	v_cvt_pk_bf16_f32 v72, v12, v13
	v_cvt_pk_bf16_f32 v73, v14, v15
	v_pk_mul_f32 v[8:9], v[84:85], v[8:9] op_sel_hi:[0,1]
	v_pk_add_f32 v[180:181], v[180:181], 1.0 op_sel_hi:[1,0]
	v_pk_mul_f32 v[8:9], v[8:9], v[116:117]
	v_pk_fma_f32 v[8:9], v[8:9], v[180:181], v[148:149]
	v_pk_mul_f32 v[10:11], v[84:85], v[10:11] op_sel_hi:[0,1]
	v_pk_add_f32 v[182:183], v[182:183], 1.0 op_sel_hi:[1,0]
	v_pk_mul_f32 v[10:11], v[10:11], v[118:119]
	v_pk_fma_f32 v[10:11], v[10:11], v[182:183], v[150:151]
	v_cvt_pk_bf16_f32 v74, v8, v9
	v_cvt_pk_bf16_f32 v75, v10, v11
	v_pk_mul_f32 v[4:5], v[84:85], v[4:5] op_sel_hi:[0,1]
	v_pk_add_f32 v[184:185], v[184:185], 1.0 op_sel_hi:[1,0]
	v_pk_mul_f32 v[4:5], v[4:5], v[120:121]
	v_pk_fma_f32 v[4:5], v[4:5], v[184:185], v[152:153]
	v_pk_mul_f32 v[6:7], v[84:85], v[6:7] op_sel_hi:[0,1]
	v_pk_add_f32 v[186:187], v[186:187], 1.0 op_sel_hi:[1,0]
	v_pk_mul_f32 v[6:7], v[6:7], v[122:123]
	v_pk_fma_f32 v[6:7], v[6:7], v[186:187], v[154:155]
	v_cvt_pk_bf16_f32 v76, v4, v5
	v_cvt_pk_bf16_f32 v77, v6, v7
	v_pk_mul_f32 v[0:1], v[84:85], v[0:1] op_sel_hi:[0,1]
	v_pk_add_f32 v[188:189], v[188:189], 1.0 op_sel_hi:[1,0]
	v_pk_mul_f32 v[0:1], v[0:1], v[124:125]
	v_pk_fma_f32 v[0:1], v[0:1], v[188:189], v[156:157]
	v_pk_mul_f32 v[2:3], v[84:85], v[2:3] op_sel_hi:[0,1]
	v_pk_add_f32 v[190:191], v[190:191], 1.0 op_sel_hi:[1,0]
	v_pk_mul_f32 v[2:3], v[2:3], v[126:127]
	v_pk_fma_f32 v[2:3], v[2:3], v[190:191], v[158:159]
	v_cvt_pk_bf16_f32 v78, v0, v1
	v_cvt_pk_bf16_f32 v79, v2, v3
	global_store_dwordx2 v[92:93], v[64:65], off
	global_store_dwordx2 v[92:93], v[66:67], off offset:512
	global_store_dwordx2 v[92:93], v[68:69], off offset:1024
	global_store_dwordx2 v[92:93], v[70:71], off offset:1536
	global_store_dwordx2 v[92:93], v[72:73], off offset:2048
	global_store_dwordx2 v[92:93], v[74:75], off offset:2560
	global_store_dwordx2 v[92:93], v[76:77], off offset:3072
	global_store_dwordx2 v[92:93], v[78:79], off offset:3584
	s_branch .Lp1_done
; __device__ __forceinline__ unsigned cvtpk(float lo, float hi) { unsigned r; asm volatile("v_cvt_pk_bf16_f32 %0, %1, %2" : "=v"(r) : "v"(lo), "v"(hi)); return r; }
; __global__ void __launch_bounds__(512, 2) fwd_megakernel(Params p) {
;     ...
;             f32x4 v[8]; float ss = 0.f;
; #pragma unroll
;             for (int j = 0; j < 8; ++j) { v[j] = __builtin_nontemporal_load((const f32x4*)(src + j * 256 + lane * 4)); ss += (v[j].x * v[j].x + v[j].y * v[j].y) + (v[j].z * v[j].z + v[j].w * v[j].w); }
;             const float rstd = rsqrtf(wave_sum(ss) * (1.f / DM) + 1e-6f);
;             bf16_t* orow = HX + (size_t)R * DM;
; #pragma unroll
;             for (int j = 0; j < 8; ++j) { const int k = j * 256 + lane * 4;
;                 const f32x4 g4 = *(const f32x4*)(p.norm_g + k), sh = *(const f32x4*)(mr + k), sc4 = *(const f32x4*)(mr + 2048 + k);
;                 const f32x4 y = v[j] * rstd * g4 * (sc4 + 1.f) + sh;
;                 uint2 w; w.x = cvtpk(y.x, y.y); w.y = cvtpk(y.z, y.w); *(uint2*)(orow + k) = w; }
.Lp1_lastB:
	s_waitcnt vmcnt(24)
	v_mul_f32_e32 v81, v203, v203
	v_mul_f32_e32 v82, v205, v205
	v_fmac_f32_e32 v81, v202, v202
	v_fmac_f32_e32 v82, v204, v204
	v_add_f32_e32 v80, v81, v82
	v_mul_f32_e32 v81, v207, v207
	v_mul_f32_e32 v82, v209, v209
	v_fmac_f32_e32 v81, v206, v206
	v_fmac_f32_e32 v82, v208, v208
	v_add_f32_e32 v81, v81, v82
	v_add_f32_e32 v80, v80, v81
	v_mul_f32_e32 v81, v211, v211
	v_mul_f32_e32 v82, v213, v213
	v_fmac_f32_e32 v81, v210, v210
	v_fmac_f32_e32 v82, v212, v212
	v_add_f32_e32 v81, v81, v82
	v_add_f32_e32 v80, v80, v81
	v_mul_f32_e32 v81, v215, v215
	v_mul_f32_e32 v82, v217, v217
	v_fmac_f32_e32 v81, v214, v214
	v_fmac_f32_e32 v82, v216, v216
	v_add_f32_e32 v81, v81, v82
	v_add_f32_e32 v80, v80, v81
	v_mul_f32_e32 v81, v219, v219
	v_mul_f32_e32 v82, v221, v221
	v_fmac_f32_e32 v81, v218, v218
	v_fmac_f32_e32 v82, v220, v220
	v_add_f32_e32 v81, v81, v82
	v_add_f32_e32 v80, v80, v81
	v_mul_f32_e32 v81, v223, v223
	v_mul_f32_e32 v82, v225, v225
	v_fmac_f32_e32 v81, v222, v222
	v_fmac_f32_e32 v82, v224, v224
	v_add_f32_e32 v81, v81, v82
	v_add_f32_e32 v80, v80, v81
	v_mul_f32_e32 v81, v233, v233
	v_mul_f32_e32 v82, v235, v235
	v_fmac_f32_e32 v81, v232, v232
	v_fmac_f32_e32 v82, v234, v234
	v_add_f32_e32 v81, v81, v82
	v_add_f32_e32 v80, v80, v81
	v_mul_f32_e32 v81, v237, v237
	v_mul_f32_e32 v82, v239, v239
	v_fmac_f32_e32 v81, v236, v236
	v_fmac_f32_e32 v82, v238, v238
	v_add_f32_e32 v81, v81, v82
	v_add_f32_e32 v80, v80, v81
	ds_bpermute_b32 v83, v42, v80
	s_waitcnt lgkmcnt(0)
	v_add_f32_e32 v80, v80, v83
	ds_bpermute_b32 v83, v43, v80
	s_waitcnt lgkmcnt(0)
	v_add_f32_e32 v80, v80, v83
	ds_bpermute_b32 v83, v44, v80
	s_waitcnt lgkmcnt(0)
	v_add_f32_e32 v80, v80, v83
	ds_bpermute_b32 v83, v45, v80
	s_waitcnt lgkmcnt(0)
	v_add_f32_e32 v80, v80, v83
	ds_bpermute_b32 v83, v46, v80
	s_waitcnt lgkmcnt(0)
	v_add_f32_e32 v80, v80, v83
	ds_bpermute_b32 v83, v47, v80
	s_waitcnt lgkmcnt(0)
	v_add_f32_e32 v80, v80, v83
	v_fmamk_f32 v80, v80, 0x3a000000, v48
	v_mul_f32_e32 v81, 0x4b800000, v80
	v_cmp_gt_f32_e32 vcc, s1, v80
	s_nop 1
	v_cndmask_b32_e32 v80, v80, v81, vcc
	v_rsq_f32_e32 v84, v80
	v_lshl_add_u64 v[92:93], v[40:41], 0, s[20:21]
	s_nop 0
	v_mul_f32_e32 v85, 0x45800000, v84
	s_nop 0
	v_cndmask_b32_e32 v84, v84, v85, vcc
	s_waitcnt vmcnt(8)
	v_pk_mul_f32 v[202:203], v[84:85], v[202:203] op_sel_hi:[0,1]
	v_pk_add_f32 v[160:161], v[160:161], 1.0 op_sel_hi:[1,0]
	v_pk_mul_f32 v[202:203], v[202:203], v[96:97]
	v_pk_fma_f32 v[202:203], v[202:203], v[160:161], v[128:129]
	v_pk_mul_f32 v[204:205], v[84:85], v[204:205] op_sel_hi:[0,1]
	v_pk_add_f32 v[162:163], v[162:163], 1.0 op_sel_hi:[1,0]
	v_pk_mul_f32 v[204:205], v[204:205], v[98:99]
	v_pk_fma_f32 v[204:205], v[204:205], v[162:163], v[130:131]
	v_cvt_pk_bf16_f32 v64, v202, v203
	v_cvt_pk_bf16_f32 v65, v204, v205
	v_pk_mul_f32 v[206:207], v[84:85], v[206:207] op_sel_hi:[0,1]
	v_pk_add_f32 v[164:165], v[164:165], 1.0 op_sel_hi:[1,0]
	v_pk_mul_f32 v[206:207], v[206:207], v[100:101]
	v_pk_fma_f32 v[206:207], v[206:207], v[164:165], v[132:133]
	v_pk_mul_f32 v[208:209], v[84:85], v[208:209] op_sel_hi:[0,1]
	v_pk_add_f32 v[166:167], v[166:167], 1.0 op_sel_hi:[1,0]
	v_pk_mul_f32 v[208:209], v[208:209], v[102:103]
	v_pk_fma_f32 v[208:209], v[208:209], v[166:167], v[134:135]
	v_cvt_pk_bf16_f32 v66, v206, v207
	v_cvt_pk_bf16_f32 v67, v208, v209
	v_pk_mul_f32 v[210:211], v[84:85], v[210:211] op_sel_hi:[0,1]
	v_pk_add_f32 v[168:169], v[168:169], 1.0 op_sel_hi:[1,0]
	v_pk_mul_f32 v[210:211], v[210:211], v[104:105]
	v_pk_fma_f32 v[210:211], v[210:211], v[168:169], v[136:137]
	v_pk_mul_f32 v[212:213], v[84:85], v[212:213] op_sel_hi:[0,1]
	v_pk_add_f32 v[170:171], v[170:171], 1.0 op_sel_hi:[1,0]
	v_pk_mul_f32 v[212:213], v[212:213], v[106:107]
	v_pk_fma_f32 v[212:213], v[212:213], v[170:171], v[138:139]
	v_cvt_pk_bf16_f32 v68, v210, v211
	v_cvt_pk_bf16_f32 v69, v212, v213
	v_pk_mul_f32 v[214:215], v[84:85], v[214:215] op_sel_hi:[0,1]
	v_pk_add_f32 v[172:173], v[172:173], 1.0 op_sel_hi:[1,0]
	v_pk_mul_f32 v[214:215], v[214:215], v[108:109]
	v_pk_fma_f32 v[214:215], v[214:215], v[172:173], v[140:141]
	v_pk_mul_f32 v[216:217], v[84:85], v[216:217] op_sel_hi:[0,1]
	v_pk_add_f32 v[174:175], v[174:175], 1.0 op_sel_hi:[1,0]
	v_pk_mul_f32 v[216:217], v[216:217], v[110:111]
	v_pk_fma_f32 v[216:217], v[216:217], v[174:175], v[142:143]
	v_cvt_pk_bf16_f32 v70, v214, v215
	v_cvt_pk_bf16_f32 v71, v216, v217
	v_pk_mul_f32 v[218:219], v[84:85], v[218:219] op_sel_hi:[0,1]
	v_pk_add_f32 v[176:177], v[176:177], 1.0 op_sel_hi:[1,0]
	v_pk_mul_f32 v[218:219], v[218:219], v[112:113]
	v_pk_fma_f32 v[218:219], v[218:219], v[176:177], v[144:145]
	v_pk_mul_f32 v[220:221], v[84:85], v[220:221] op_sel_hi:[0,1]
	v_pk_add_f32 v[178:179], v[178:179], 1.0 op_sel_hi:[1,0]
	v_pk_mul_f32 v[220:221], v[220:221], v[114:115]
	v_pk_fma_f32 v[220:221], v[220:221], v[178:179], v[146:147]
	v_cvt_pk_bf16_f32 v72, v218, v219
	v_cvt_pk_bf16_f32 v73, v220, v221
	v_pk_mul_f32 v[222:223], v[84:85], v[222:223] op_sel_hi:[0,1]
	v_pk_add_f32 v[180:181], v[180:181], 1.0 op_sel_hi:[1,0]
	v_pk_mul_f32 v[222:223], v[222:223], v[116:117]
	v_pk_fma_f32 v[222:223], v[222:223], v[180:181], v[148:149]
	v_pk_mul_f32 v[224:225], v[84:85], v[224:225] op_sel_hi:[0,1]
	v_pk_add_f32 v[182:183], v[182:183], 1.0 op_sel_hi:[1,0]
	v_pk_mul_f32 v[224:225], v[224:225], v[118:119]
	v_pk_fma_f32 v[224:225], v[224:225], v[182:183], v[150:151]
	v_cvt_pk_bf16_f32 v74, v222, v223
	v_cvt_pk_bf16_f32 v75, v224, v225
	v_pk_mul_f32 v[232:233], v[84:85], v[232:233] op_sel_hi:[0,1]
	v_pk_add_f32 v[184:185], v[184:185], 1.0 op_sel_hi:[1,0]
	v_pk_mul_f32 v[232:233], v[232:233], v[120:121]
	v_pk_fma_f32 v[232:233], v[232:233], v[184:185], v[152:153]
	v_pk_mul_f32 v[234:235], v[84:85], v[234:235] op_sel_hi:[0,1]
	v_pk_add_f32 v[186:187], v[186:187], 1.0 op_sel_hi:[1,0]
	v_pk_mul_f32 v[234:235], v[234:235], v[122:123]
	v_pk_fma_f32 v[234:235], v[234:235], v[186:187], v[154:155]
	v_cvt_pk_bf16_f32 v76, v232, v233
	v_cvt_pk_bf16_f32 v77, v234, v235
	v_pk_mul_f32 v[236:237], v[84:85], v[236:237] op_sel_hi:[0,1]
	v_pk_add_f32 v[188:189], v[188:189], 1.0 op_sel_hi:[1,0]
	v_pk_mul_f32 v[236:237], v[236:237], v[124:125]
	v_pk_fma_f32 v[236:237], v[236:237], v[188:189], v[156:157]
	v_pk_mul_f32 v[238:239], v[84:85], v[238:239] op_sel_hi:[0,1]
	v_pk_add_f32 v[190:191], v[190:191], 1.0 op_sel_hi:[1,0]
	v_pk_mul_f32 v[238:239], v[238:239], v[126:127]
	v_pk_fma_f32 v[238:239], v[238:239], v[190:191], v[158:159]
	v_cvt_pk_bf16_f32 v78, v236, v237
	v_cvt_pk_bf16_f32 v79, v238, v239
	global_store_dwordx2 v[92:93], v[64:65], off
	global_store_dwordx2 v[92:93], v[66:67], off offset:512
	global_store_dwordx2 v[92:93], v[68:69], off offset:1024
	global_store_dwordx2 v[92:93], v[70:71], off offset:1536
	global_store_dwordx2 v[92:93], v[72:73], off offset:2048
	global_store_dwordx2 v[92:93], v[74:75], off offset:2560
	global_store_dwordx2 v[92:93], v[76:77], off offset:3072
	global_store_dwordx2 v[92:93], v[78:79], off offset:3584
; __global__ void __launch_bounds__(512, 2) fwd_megakernel(Params p) {
;     ...
;     grid.sync();
.Lp1_done:
.LBB0_62:
	s_waitcnt vmcnt(0)
	s_barrier
	s_mov_b64 s[4:5], exec
	v_readlane_b32 s0, v254, 18
	v_readlane_b32 s1, v254, 19
	s_and_b64 s[0:1], s[4:5], s[0:1]
	s_mov_b64 exec, s[0:1]
	s_cbranch_execz .LBB0_72
	v_readlane_b32 s0, v254, 16
	v_readlane_b32 s1, v254, 17
	buffer_wbl2 sc1
	s_waitcnt vmcnt(0)
	s_sub_u32 s0, s0, 8
	s_subb_u32 s1, s1, 0
	s_load_dwordx2 s[0:1], s[0:1], 0x0
	v_mov_b32_e32 v2, 0
	v_mov_b32_e32 v3, 1
	s_waitcnt lgkmcnt(0)
	s_add_u32 s0, s0, 0x1e400
	s_addc_u32 s1, s1, 0
	global_atomic_add v2, v3, s[0:1]
